# stack21 + barrier poll tightening: s_sleep 1 in the seam-barrier spin loops replaced by s_nop 7
# baseline (speedup 1.0000x reference)
.LBB0_42:
	v_readlane_b32 s0, v251, 18
	v_readlane_b32 s1, v251, 19
	s_mov_b64 s[16:17], -1
	s_waitcnt lgkmcnt(0)
	s_nop 2
	global_load_dword v9, v1, s[0:1] sc1
	v_readlane_b32 s0, v251, 20
	v_readlane_b32 s1, v251, 21
	s_waitcnt vmcnt(0)
	v_readfirstlane_b32 s13, v9
	s_nop 2
	global_load_dword v10, v1, s[0:1] sc1
	v_readlane_b32 s0, v251, 22
	v_readlane_b32 s1, v251, 23
	s_and_b32 s19, s13, 0x1ff
	s_waitcnt vmcnt(0)
	v_readfirstlane_b32 s12, v10
	s_nop 1
	global_load_dword v25, v1, s[0:1] sc1
	v_readlane_b32 s0, v251, 24
	v_readlane_b32 s1, v251, 25
	s_and_b32 s18, s12, 0x1ff
	s_add_i32 s4, s18, s19
	s_waitcnt vmcnt(0)
	v_and_b32_e32 v21, 0x1ff, v25
	s_nop 0
	global_load_dword v11, v1, s[0:1] sc1
	v_readlane_b32 s0, v251, 26
	v_readlane_b32 s1, v251, 27
	v_add_u32_e32 v26, s4, v21
	v_readlane_b32 s4, v251, 51
	s_waitcnt vmcnt(0)
	v_and_b32_e32 v22, 0x1ff, v11
	s_nop 0
	global_load_dword v24, v1, s[0:1] sc1
	v_readlane_b32 s0, v251, 28
	v_readlane_b32 s1, v251, 29
	v_add_u32_e32 v26, v26, v22
	v_readfirstlane_b32 s30, v11
	s_waitcnt vmcnt(0)
	v_and_b32_e32 v19, 0x1ff, v24
	s_nop 0
	global_load_dword v12, v1, s[0:1] sc1
	v_readlane_b32 s0, v251, 30
	v_readlane_b32 s1, v251, 31
	v_add_u32_e32 v26, v26, v19
	s_waitcnt vmcnt(0)
	v_and_b32_e32 v20, 0x1ff, v12
	s_nop 1
	global_load_dword v23, v1, s[0:1] sc1
	v_readlane_b32 s0, v251, 32
	v_readlane_b32 s1, v251, 33
	v_add_u32_e32 v26, v26, v20
	v_readfirstlane_b32 s29, v12
	s_waitcnt vmcnt(0)
	v_and_b32_e32 v17, 0x1ff, v23
	s_nop 0
	global_load_dword v13, v1, s[0:1] sc1
	v_readlane_b32 s0, v251, 34
	v_readlane_b32 s1, v251, 35
	v_add_u32_e32 v26, v26, v17
	s_waitcnt vmcnt(0)
	v_and_b32_e32 v18, 0x1ff, v13
	s_nop 1
	global_load_dword v0, v1, s[0:1] sc1
	v_readlane_b32 s0, v251, 36
	v_readlane_b32 s1, v251, 37
	v_add_u32_e32 v26, v26, v18
	v_readfirstlane_b32 s23, v13
	s_waitcnt vmcnt(0)
	v_and_b32_e32 v16, 0x1ff, v0
	s_nop 0
	global_load_dword v2, v1, s[0:1] sc1
	v_readlane_b32 s0, v251, 38
	v_readlane_b32 s1, v251, 39
	v_add_u32_e32 v26, v26, v16
	s_waitcnt vmcnt(0)
	v_and_b32_e32 v15, 0x1ff, v2
	s_nop 1
	global_load_dword v3, v1, s[0:1] sc1
	v_readlane_b32 s0, v251, 40
	v_readlane_b32 s1, v251, 41
	v_add_u32_e32 v26, v26, v15
	s_waitcnt vmcnt(0)
	v_and_b32_e32 v14, 0x1ff, v3
	s_nop 1
	global_load_dword v4, v1, s[0:1] sc1
	v_readlane_b32 s0, v251, 42
	v_readlane_b32 s1, v251, 43
	v_add_u32_e32 v26, v26, v14
	s_waitcnt vmcnt(0)
	v_and_b32_e32 v13, 0x1ff, v4
	s_nop 1
	global_load_dword v5, v1, s[0:1] sc1
	v_readlane_b32 s0, v251, 44
	v_readlane_b32 s1, v251, 45
	v_add_u32_e32 v26, v26, v13
	s_waitcnt vmcnt(0)
	v_and_b32_e32 v12, 0x1ff, v5
	s_nop 1
	global_load_dword v6, v1, s[0:1] sc1
	v_readlane_b32 s0, v251, 46
	v_readlane_b32 s1, v251, 47
	v_add_u32_e32 v26, v26, v12
	s_waitcnt vmcnt(0)
	v_and_b32_e32 v11, 0x1ff, v6
	s_nop 1
	global_load_dword v7, v1, s[0:1] sc1
	v_readlane_b32 s0, v251, 48
	v_readlane_b32 s1, v251, 49
	v_add_u32_e32 v26, v26, v11
	s_waitcnt vmcnt(0)
	v_and_b32_e32 v10, 0x1ff, v7
	s_nop 1
	global_load_dword v8, v1, s[0:1] sc1
	v_add_u32_e32 v26, v26, v10
	s_mov_b64 s[0:1], -1
	s_waitcnt vmcnt(0)
	v_and_b32_e32 v9, 0x1ff, v8
	v_add_u32_e32 v26, v26, v9
	v_cmp_eq_u32_e32 vcc, s4, v26
	s_mov_b64 s[4:5], -1
	s_cbranch_vccnz .LBB0_41
	s_and_b32 s0, s8, 0xff
	s_cmp_eq_u32 s0, 0
	s_mov_b64 s[0:1], -1
	s_mov_b64 s[6:7], -1
	s_nop 7
	s_cbranch_scc0 .LBB0_45
	v_readlane_b32 s0, v251, 16
	v_readlane_b32 s1, v251, 17
	s_mov_b64 s[16:17], 0
	s_mov_b64 s[6:7], 0
	s_nop 2
	global_load_dword v26, v1, s[0:1] sc1
	s_mov_b64 s[0:1], -1
	s_waitcnt vmcnt(0)
	v_cmp_eq_u32_e32 vcc, 0, v26
	s_cbranch_vccnz .LBB0_47

.LBB0_57:
	s_and_b32 s19, s18, 0xff
	s_mov_b64 s[16:17], -1
	s_cmp_lg_u32 s19, 0
	s_mov_b64 s[52:53], -1
	s_nop 7
	s_cbranch_scc0 .LBB0_60
	s_and_b64 vcc, exec, s[52:53]
	s_cbranch_vccz .LBB0_56

.LBB0_74:
	s_and_b32 s16, s18, 0xff
	s_mov_b64 s[12:13], -1
	s_cmp_lg_u32 s16, 0
	s_mov_b64 s[20:21], -1
	s_nop 7
	s_cbranch_scc0 .LBB0_77
	s_and_b64 vcc, exec, s[20:21]
	s_cbranch_vccz .LBB0_73

.LBB0_92:
	s_and_b32 s14, s18, 0xff
	s_mov_b64 s[12:13], -1
	s_cmp_lg_u32 s14, 0
	s_mov_b64 s[16:17], -1
	s_nop 7
	s_cbranch_scc0 .LBB0_95
	s_and_b64 vcc, exec, s[16:17]
	s_cbranch_vccz .LBB0_91

.LBB0_108:
	s_nop 7
	global_load_dword v2, v1, s[2:3] offset:32 sc1
	s_waitcnt vmcnt(0)
	v_and_b32_e32 v2, 0xffff0000, v2
	v_cmp_ne_u32_e32 vcc, v2, v0
	s_or_b64 s[4:5], vcc, s[4:5]
	s_andn2_b64 exec, exec, s[4:5]
	s_cbranch_execnz .LBB0_108
